# GEMM K-loop: A-fragment ds_read base addresses computed once per tile instead of 4 VALU adds per iteration in front of the reads
# speedup vs baseline: 1.0024x; 1.0024x over previous
.LBB0_246:
	s_andn2_b64 vcc, exec, s[18:19]
	s_cbranch_vccnz .Lk_zero_skip
	v_add_u32_e32 v236, 0x10000, v227
	v_add_u32_e32 v237, 0x14000, v227
	v_add_u32_e32 v238, 0x18000, v227
	v_add_u32_e32 v239, 0x1c000, v227
	s_add_u32 s44, s44, 0x80
	s_addc_u32 s45, s45, 0
	s_add_u32 s23, s46, 0x100
	s_addc_u32 s48, s47, 0
	s_mov_b32 s46, 0
	s_add_i32 s49, s46, 2
	s_add_u32 s69, s44, 0x80
	s_addc_u32 s47, s45, 0
	s_add_i32 s80, 0, 0x10000
	s_cmp_eq_u32 s90, s46
	s_cselect_b32 s47, s65, s47
	s_cselect_b32 s46, s64, s69
	s_cselect_b32 s71, s67, s48
	s_cselect_b32 s70, s66, s23
	s_add_i32 s69, 0, 0x14000
	ds_read_b128 v[128:131], v236
	ds_read_b128 v[132:135], v236 offset:1024
	ds_read_b128 v[136:139], v236 offset:2048
	ds_read_b128 v[140:143], v236 offset:3072
	ds_read_b128 v[144:147], v237
	ds_read_b128 v[148:151], v237 offset:1024
	ds_read_b128 v[174:177], v237 offset:2048
	ds_read_b128 v[178:181], v237 offset:3072
	s_add_i32 m0, s50, 0xc000
	ds_read_b128 v[182:185], v230
	ds_read_b128 v[186:189], v230 offset:1024
	ds_read_b128 v[190:193], v230 offset:2048
	ds_read_b128 v[194:197], v230 offset:3072
	ds_read_b128 v[198:201], v230 offset:4096
	ds_read_b128 v[202:205], v230 offset:5120
	ds_read_b128 v[206:209], v230 offset:6144
	ds_read_b128 v[232:235], v230 offset:7168
	global_load_lds_dwordx4 v170, s[44:45]
	s_add_i32 m0, s50, 0xe000
	s_nop 0
	global_load_lds_dwordx4 v172, s[44:45]
	s_waitcnt vmcnt(8)
	s_waitcnt lgkmcnt(0)
	s_barrier
	s_setprio 1
	s_waitcnt lgkmcnt(0)
	v_mfma_f32_16x16x32_bf16 v[16:19], v[128:131], v[182:185], 0
	v_mfma_f32_16x16x32_bf16 v[28:31], v[136:139], v[182:185], 0
	v_mfma_f32_16x16x32_bf16 v[12:15], v[128:131], v[190:193], 0
	v_mfma_f32_16x16x32_bf16 v[8:11], v[136:139], v[190:193], 0
	v_mfma_f32_16x16x32_bf16 v[124:127], v[128:131], v[198:201], 0
	v_mfma_f32_16x16x32_bf16 v[120:123], v[136:139], v[198:201], 0
	v_mfma_f32_16x16x32_bf16 v[108:111], v[128:131], v[206:209], 0
	v_mfma_f32_16x16x32_bf16 v[104:107], v[136:139], v[206:209], 0
	v_mfma_f32_16x16x32_bf16 v[16:19], v[132:135], v[186:189], v[16:19]
	v_mfma_f32_16x16x32_bf16 v[28:31], v[140:143], v[186:189], v[28:31]
	v_mfma_f32_16x16x32_bf16 v[12:15], v[132:135], v[194:197], v[12:15]
	v_mfma_f32_16x16x32_bf16 v[8:11], v[140:143], v[194:197], v[8:11]
	v_mfma_f32_16x16x32_bf16 v[124:127], v[132:135], v[202:205], v[124:127]
	v_mfma_f32_16x16x32_bf16 v[120:123], v[140:143], v[202:205], v[120:123]
	v_mfma_f32_16x16x32_bf16 v[108:111], v[132:135], v[232:235], v[108:111]
	v_mfma_f32_16x16x32_bf16 v[104:107], v[140:143], v[232:235], v[104:107]
	s_setprio 0
	s_setprio 1
	v_mfma_f32_16x16x32_bf16 v[24:27], v[144:147], v[182:185], 0
	v_mfma_f32_16x16x32_bf16 v[20:23], v[174:177], v[182:185], 0
	v_mfma_f32_16x16x32_bf16 v[4:7], v[144:147], v[190:193], 0
	v_mfma_f32_16x16x32_bf16 v[0:3], v[174:177], v[190:193], 0
	v_mfma_f32_16x16x32_bf16 v[116:119], v[144:147], v[198:201], 0
	v_mfma_f32_16x16x32_bf16 v[112:115], v[174:177], v[198:201], 0
	v_mfma_f32_16x16x32_bf16 v[100:103], v[144:147], v[206:209], 0
	v_mfma_f32_16x16x32_bf16 v[96:99], v[174:177], v[206:209], 0
	v_mfma_f32_16x16x32_bf16 v[24:27], v[148:151], v[186:189], v[24:27]
	v_mfma_f32_16x16x32_bf16 v[20:23], v[178:181], v[186:189], v[20:23]
	v_mfma_f32_16x16x32_bf16 v[4:7], v[148:151], v[194:197], v[4:7]
	v_mfma_f32_16x16x32_bf16 v[0:3], v[178:181], v[194:197], v[0:3]
	v_mfma_f32_16x16x32_bf16 v[116:119], v[148:151], v[202:205], v[116:119]
	v_mfma_f32_16x16x32_bf16 v[112:115], v[178:181], v[202:205], v[112:115]
	v_mfma_f32_16x16x32_bf16 v[100:103], v[148:151], v[232:235], v[100:103]
	v_mfma_f32_16x16x32_bf16 v[96:99], v[178:181], v[232:235], v[96:99]
	s_setprio 0
	s_barrier
	s_add_i32 s80, s80, s3
	s_mov_b32 m0, s80
	ds_read_b128 v[182:185], v230 offset:16384
	ds_read_b128 v[186:189], v230 offset:17408
	ds_read_b128 v[190:193], v230 offset:18432
	ds_read_b128 v[194:197], v230 offset:19456
	ds_read_b128 v[198:201], v230 offset:20480
	ds_read_b128 v[202:205], v230 offset:21504
	ds_read_b128 v[206:209], v230 offset:22528
	ds_read_b128 v[232:235], v230 offset:23552
	global_load_lds_dwordx4 v160, s[70:71]
	s_add_i32 m0, s80, 0x2000
	s_add_i32 s69, s69, s3
	global_load_lds_dwordx4 v164, s[70:71]
	s_add_u32 s70, s70, s26
	s_addc_u32 s71, s71, 0
	s_mov_b32 m0, s69
	s_nop 0
	global_load_lds_dwordx4 v160, s[70:71]
	s_add_i32 m0, s69, 0x2000
	s_nop 0
	global_load_lds_dwordx4 v164, s[70:71]
	s_mov_b32 m0, s50
	s_nop 0
	global_load_lds_dwordx4 v158, s[46:47]
	s_mov_b32 m0, s51
	s_nop 0
	global_load_lds_dwordx4 v162, s[46:47]
	s_waitcnt vmcnt(8)
	s_waitcnt lgkmcnt(0)
	s_barrier
	s_setprio 1
	s_waitcnt lgkmcnt(0)
	v_mfma_f32_16x16x32_bf16 v[92:95], v[128:131], v[182:185], 0
	v_mfma_f32_16x16x32_bf16 v[88:91], v[136:139], v[182:185], 0
	v_mfma_f32_16x16x32_bf16 v[76:79], v[128:131], v[190:193], 0
	v_mfma_f32_16x16x32_bf16 v[72:75], v[136:139], v[190:193], 0
	v_mfma_f32_16x16x32_bf16 v[60:63], v[128:131], v[198:201], 0
	v_mfma_f32_16x16x32_bf16 v[56:59], v[136:139], v[198:201], 0
	v_mfma_f32_16x16x32_bf16 v[44:47], v[128:131], v[206:209], 0
	v_mfma_f32_16x16x32_bf16 v[40:43], v[136:139], v[206:209], 0
	v_mfma_f32_16x16x32_bf16 v[92:95], v[132:135], v[186:189], v[92:95]
	v_mfma_f32_16x16x32_bf16 v[88:91], v[140:143], v[186:189], v[88:91]
	v_mfma_f32_16x16x32_bf16 v[76:79], v[132:135], v[194:197], v[76:79]
	v_mfma_f32_16x16x32_bf16 v[72:75], v[140:143], v[194:197], v[72:75]
	v_mfma_f32_16x16x32_bf16 v[60:63], v[132:135], v[202:205], v[60:63]
	v_mfma_f32_16x16x32_bf16 v[56:59], v[140:143], v[202:205], v[56:59]
	v_mfma_f32_16x16x32_bf16 v[44:47], v[132:135], v[232:235], v[44:47]
	v_mfma_f32_16x16x32_bf16 v[40:43], v[140:143], v[232:235], v[40:43]
	s_setprio 0
	s_setprio 1
	v_mfma_f32_16x16x32_bf16 v[84:87], v[144:147], v[182:185], 0
	v_mfma_f32_16x16x32_bf16 v[80:83], v[174:177], v[182:185], 0
	v_mfma_f32_16x16x32_bf16 v[68:71], v[144:147], v[190:193], 0
	v_mfma_f32_16x16x32_bf16 v[64:67], v[174:177], v[190:193], 0
	v_mfma_f32_16x16x32_bf16 v[52:55], v[144:147], v[198:201], 0
	v_mfma_f32_16x16x32_bf16 v[48:51], v[174:177], v[198:201], 0
	v_mfma_f32_16x16x32_bf16 v[36:39], v[144:147], v[206:209], 0
	v_mfma_f32_16x16x32_bf16 v[32:35], v[174:177], v[206:209], 0
	v_mfma_f32_16x16x32_bf16 v[84:87], v[148:151], v[186:189], v[84:87]
	v_mfma_f32_16x16x32_bf16 v[80:83], v[178:181], v[186:189], v[80:83]
	v_mfma_f32_16x16x32_bf16 v[68:71], v[148:151], v[194:197], v[68:71]
	v_mfma_f32_16x16x32_bf16 v[64:67], v[178:181], v[194:197], v[64:67]
	v_mfma_f32_16x16x32_bf16 v[52:55], v[148:151], v[202:205], v[52:55]
	v_mfma_f32_16x16x32_bf16 v[48:51], v[178:181], v[202:205], v[48:51]
	v_mfma_f32_16x16x32_bf16 v[36:39], v[148:151], v[232:235], v[36:39]
	v_mfma_f32_16x16x32_bf16 v[32:35], v[178:181], v[232:235], v[32:35]
	s_setprio 0
	s_barrier
	ds_read_b128 v[128:131], v238
	ds_read_b128 v[132:135], v238 offset:1024
	ds_read_b128 v[136:139], v238 offset:2048
	ds_read_b128 v[140:143], v238 offset:3072
	ds_read_b128 v[144:147], v239
	ds_read_b128 v[148:151], v239 offset:1024
	ds_read_b128 v[174:177], v239 offset:2048
	ds_read_b128 v[178:181], v239 offset:3072
	s_add_u32 s46, s46, s26
	s_addc_u32 s47, s47, 0
	s_mov_b32 m0, s8
	ds_read_b128 v[182:185], v230 offset:32768
	ds_read_b128 v[186:189], v230 offset:33792
	ds_read_b128 v[190:193], v230 offset:34816
	ds_read_b128 v[194:197], v230 offset:35840
	ds_read_b128 v[198:201], v230 offset:36864
	ds_read_b128 v[202:205], v230 offset:37888
	ds_read_b128 v[206:209], v230 offset:38912
	ds_read_b128 v[232:235], v230 offset:39936
	global_load_lds_dwordx4 v158, s[46:47]
	s_mov_b32 m0, s9
	s_nop 0
	global_load_lds_dwordx4 v162, s[46:47]
	s_waitcnt vmcnt(8)
	s_waitcnt lgkmcnt(0)
	s_barrier
	s_setprio 1
	s_waitcnt lgkmcnt(0)
	v_mfma_f32_16x16x32_bf16 v[16:19], v[128:131], v[182:185], v[16:19]
	v_mfma_f32_16x16x32_bf16 v[28:31], v[136:139], v[182:185], v[28:31]
	v_mfma_f32_16x16x32_bf16 v[12:15], v[128:131], v[190:193], v[12:15]
	v_mfma_f32_16x16x32_bf16 v[8:11], v[136:139], v[190:193], v[8:11]
	v_mfma_f32_16x16x32_bf16 v[124:127], v[128:131], v[198:201], v[124:127]
	v_mfma_f32_16x16x32_bf16 v[120:123], v[136:139], v[198:201], v[120:123]
	v_mfma_f32_16x16x32_bf16 v[108:111], v[128:131], v[206:209], v[108:111]
	v_mfma_f32_16x16x32_bf16 v[104:107], v[136:139], v[206:209], v[104:107]
	v_mfma_f32_16x16x32_bf16 v[16:19], v[132:135], v[186:189], v[16:19]
	v_mfma_f32_16x16x32_bf16 v[28:31], v[140:143], v[186:189], v[28:31]
	v_mfma_f32_16x16x32_bf16 v[12:15], v[132:135], v[194:197], v[12:15]
	v_mfma_f32_16x16x32_bf16 v[8:11], v[140:143], v[194:197], v[8:11]
	v_mfma_f32_16x16x32_bf16 v[124:127], v[132:135], v[202:205], v[124:127]
	v_mfma_f32_16x16x32_bf16 v[120:123], v[140:143], v[202:205], v[120:123]
	v_mfma_f32_16x16x32_bf16 v[108:111], v[132:135], v[232:235], v[108:111]
	v_mfma_f32_16x16x32_bf16 v[104:107], v[140:143], v[232:235], v[104:107]
	s_setprio 0
	s_setprio 1
	v_mfma_f32_16x16x32_bf16 v[24:27], v[144:147], v[182:185], v[24:27]
	v_mfma_f32_16x16x32_bf16 v[20:23], v[174:177], v[182:185], v[20:23]
	v_mfma_f32_16x16x32_bf16 v[4:7], v[144:147], v[190:193], v[4:7]
	v_mfma_f32_16x16x32_bf16 v[0:3], v[174:177], v[190:193], v[0:3]
	v_mfma_f32_16x16x32_bf16 v[116:119], v[144:147], v[198:201], v[116:119]
	v_mfma_f32_16x16x32_bf16 v[112:115], v[174:177], v[198:201], v[112:115]
	v_mfma_f32_16x16x32_bf16 v[100:103], v[144:147], v[206:209], v[100:103]
	v_mfma_f32_16x16x32_bf16 v[96:99], v[174:177], v[206:209], v[96:99]
	v_mfma_f32_16x16x32_bf16 v[24:27], v[148:151], v[186:189], v[24:27]
	v_mfma_f32_16x16x32_bf16 v[20:23], v[178:181], v[186:189], v[20:23]
	v_mfma_f32_16x16x32_bf16 v[4:7], v[148:151], v[194:197], v[4:7]
	v_mfma_f32_16x16x32_bf16 v[0:3], v[178:181], v[194:197], v[0:3]
	v_mfma_f32_16x16x32_bf16 v[116:119], v[148:151], v[202:205], v[116:119]
	v_mfma_f32_16x16x32_bf16 v[112:115], v[178:181], v[202:205], v[112:115]
	v_mfma_f32_16x16x32_bf16 v[100:103], v[148:151], v[232:235], v[100:103]
	v_mfma_f32_16x16x32_bf16 v[96:99], v[178:181], v[232:235], v[96:99]
	s_setprio 0
	s_barrier
	s_add_u32 vcc_lo, s70, s6
	s_addc_u32 vcc_hi, s71, s7
	s_sub_u32 vcc_lo, vcc_lo, s26
	s_subb_u32 vcc_hi, vcc_hi, 0
	s_add_i32 m0, s3, 0x18000
	ds_read_b128 v[182:185], v230 offset:49152
	ds_read_b128 v[186:189], v230 offset:50176
	ds_read_b128 v[190:193], v230 offset:51200
	ds_read_b128 v[194:197], v230 offset:52224
	ds_read_b128 v[198:201], v230 offset:53248
	ds_read_b128 v[202:205], v230 offset:54272
	ds_read_b128 v[206:209], v230 offset:55296
	ds_read_b128 v[232:235], v230 offset:56320
	global_load_lds_dwordx4 v160, vcc
	s_add_i32 m0, s3, 0x1a000
	s_nop 0
	global_load_lds_dwordx4 v164, vcc
	s_add_u32 vcc_lo, vcc_lo, s26
	s_addc_u32 vcc_hi, vcc_hi, 0
	s_add_i32 m0, s3, 0x1c000
	s_nop 0
	global_load_lds_dwordx4 v160, vcc
	s_add_i32 m0, s3, 0x1e000
	s_nop 0
	global_load_lds_dwordx4 v164, vcc
	s_add_u32 vcc_lo, s46, s6
	s_addc_u32 vcc_hi, s47, s7
	s_sub_u32 vcc_lo, vcc_lo, s26
	s_subb_u32 vcc_hi, vcc_hi, 0
	s_mov_b32 m0, s30
	s_nop 0
	global_load_lds_dwordx4 v158, vcc
	s_mov_b32 m0, s31
	s_nop 0
	global_load_lds_dwordx4 v162, vcc
	s_waitcnt vmcnt(8)
	s_waitcnt lgkmcnt(0)
	s_barrier
	s_setprio 1
	s_waitcnt lgkmcnt(0)
	v_mfma_f32_16x16x32_bf16 v[92:95], v[128:131], v[182:185], v[92:95]
	v_mfma_f32_16x16x32_bf16 v[88:91], v[136:139], v[182:185], v[88:91]
	v_mfma_f32_16x16x32_bf16 v[76:79], v[128:131], v[190:193], v[76:79]
	v_mfma_f32_16x16x32_bf16 v[72:75], v[136:139], v[190:193], v[72:75]
	v_mfma_f32_16x16x32_bf16 v[60:63], v[128:131], v[198:201], v[60:63]
	v_mfma_f32_16x16x32_bf16 v[56:59], v[136:139], v[198:201], v[56:59]
	v_mfma_f32_16x16x32_bf16 v[44:47], v[128:131], v[206:209], v[44:47]
	v_mfma_f32_16x16x32_bf16 v[40:43], v[136:139], v[206:209], v[40:43]
	v_mfma_f32_16x16x32_bf16 v[92:95], v[132:135], v[186:189], v[92:95]
	v_mfma_f32_16x16x32_bf16 v[88:91], v[140:143], v[186:189], v[88:91]
	v_mfma_f32_16x16x32_bf16 v[76:79], v[132:135], v[194:197], v[76:79]
	v_mfma_f32_16x16x32_bf16 v[72:75], v[140:143], v[194:197], v[72:75]
	v_mfma_f32_16x16x32_bf16 v[60:63], v[132:135], v[202:205], v[60:63]
	v_mfma_f32_16x16x32_bf16 v[56:59], v[140:143], v[202:205], v[56:59]
	v_mfma_f32_16x16x32_bf16 v[44:47], v[132:135], v[232:235], v[44:47]
	v_mfma_f32_16x16x32_bf16 v[40:43], v[140:143], v[232:235], v[40:43]
	s_setprio 0
	s_setprio 1
	v_mfma_f32_16x16x32_bf16 v[84:87], v[144:147], v[182:185], v[84:87]
	v_mfma_f32_16x16x32_bf16 v[80:83], v[174:177], v[182:185], v[80:83]
	v_mfma_f32_16x16x32_bf16 v[68:71], v[144:147], v[190:193], v[68:71]
	v_mfma_f32_16x16x32_bf16 v[64:67], v[174:177], v[190:193], v[64:67]
	v_mfma_f32_16x16x32_bf16 v[52:55], v[144:147], v[198:201], v[52:55]
	v_mfma_f32_16x16x32_bf16 v[48:51], v[174:177], v[198:201], v[48:51]
	v_mfma_f32_16x16x32_bf16 v[36:39], v[144:147], v[206:209], v[36:39]
	v_mfma_f32_16x16x32_bf16 v[32:35], v[174:177], v[206:209], v[32:35]
	v_mfma_f32_16x16x32_bf16 v[84:87], v[148:151], v[186:189], v[84:87]
	v_mfma_f32_16x16x32_bf16 v[80:83], v[178:181], v[186:189], v[80:83]
	v_mfma_f32_16x16x32_bf16 v[68:71], v[148:151], v[194:197], v[68:71]
	v_mfma_f32_16x16x32_bf16 v[64:67], v[178:181], v[194:197], v[64:67]
	v_mfma_f32_16x16x32_bf16 v[52:55], v[148:151], v[202:205], v[52:55]
	v_mfma_f32_16x16x32_bf16 v[48:51], v[178:181], v[202:205], v[48:51]
	v_mfma_f32_16x16x32_bf16 v[36:39], v[148:151], v[232:235], v[36:39]
	v_mfma_f32_16x16x32_bf16 v[32:35], v[178:181], v[232:235], v[32:35]
	s_setprio 0
	s_barrier
	s_add_u32 s44, s44, 0x100
	s_addc_u32 s45, s45, 0
	s_add_u32 s23, s23, 0x100
	s_addc_u32 s48, s48, 0
	s_cmp_ge_u32 s49, s88
	s_mov_b32 s46, s49
	s_cbranch_scc1 .LBB0_249
.LBB0_248:
	s_add_i32 s49, s46, 2
	s_add_u32 s69, s44, 0x80
	s_addc_u32 s47, s45, 0
	s_add_i32 s80, 0, 0x10000
	s_cmp_eq_u32 s90, s46
	s_cselect_b32 s47, s65, s47
	s_cselect_b32 s46, s64, s69
	s_cselect_b32 s71, s67, s48
	s_cselect_b32 s70, s66, s23
	s_add_i32 s69, 0, 0x14000
	ds_read_b128 v[128:131], v236
	ds_read_b128 v[132:135], v236 offset:1024
	ds_read_b128 v[136:139], v236 offset:2048
	ds_read_b128 v[140:143], v236 offset:3072
	ds_read_b128 v[144:147], v237
	ds_read_b128 v[148:151], v237 offset:1024
	ds_read_b128 v[174:177], v237 offset:2048
	ds_read_b128 v[178:181], v237 offset:3072
	s_add_i32 m0, s50, 0xc000
	ds_read_b128 v[182:185], v230
	ds_read_b128 v[186:189], v230 offset:1024
	ds_read_b128 v[190:193], v230 offset:2048
	ds_read_b128 v[194:197], v230 offset:3072
	ds_read_b128 v[198:201], v230 offset:4096
	ds_read_b128 v[202:205], v230 offset:5120
	ds_read_b128 v[206:209], v230 offset:6144
	ds_read_b128 v[232:235], v230 offset:7168
	global_load_lds_dwordx4 v170, s[44:45]
	s_add_i32 m0, s50, 0xe000
	s_nop 0
	global_load_lds_dwordx4 v172, s[44:45]
	s_waitcnt vmcnt(8)
	s_waitcnt lgkmcnt(0)
	s_barrier
	s_setprio 1
	s_waitcnt lgkmcnt(0)
	v_mfma_f32_16x16x32_bf16 v[16:19], v[128:131], v[182:185], v[16:19]
	v_mfma_f32_16x16x32_bf16 v[28:31], v[136:139], v[182:185], v[28:31]
	v_mfma_f32_16x16x32_bf16 v[12:15], v[128:131], v[190:193], v[12:15]
	v_mfma_f32_16x16x32_bf16 v[8:11], v[136:139], v[190:193], v[8:11]
	v_mfma_f32_16x16x32_bf16 v[124:127], v[128:131], v[198:201], v[124:127]
	v_mfma_f32_16x16x32_bf16 v[120:123], v[136:139], v[198:201], v[120:123]
	v_mfma_f32_16x16x32_bf16 v[108:111], v[128:131], v[206:209], v[108:111]
	v_mfma_f32_16x16x32_bf16 v[104:107], v[136:139], v[206:209], v[104:107]
	v_mfma_f32_16x16x32_bf16 v[16:19], v[132:135], v[186:189], v[16:19]
	v_mfma_f32_16x16x32_bf16 v[28:31], v[140:143], v[186:189], v[28:31]
	v_mfma_f32_16x16x32_bf16 v[12:15], v[132:135], v[194:197], v[12:15]
	v_mfma_f32_16x16x32_bf16 v[8:11], v[140:143], v[194:197], v[8:11]
	v_mfma_f32_16x16x32_bf16 v[124:127], v[132:135], v[202:205], v[124:127]
	v_mfma_f32_16x16x32_bf16 v[120:123], v[140:143], v[202:205], v[120:123]
	v_mfma_f32_16x16x32_bf16 v[108:111], v[132:135], v[232:235], v[108:111]
	v_mfma_f32_16x16x32_bf16 v[104:107], v[140:143], v[232:235], v[104:107]
	s_setprio 0
	s_setprio 1
	v_mfma_f32_16x16x32_bf16 v[24:27], v[144:147], v[182:185], v[24:27]
	v_mfma_f32_16x16x32_bf16 v[20:23], v[174:177], v[182:185], v[20:23]
	v_mfma_f32_16x16x32_bf16 v[4:7], v[144:147], v[190:193], v[4:7]
	v_mfma_f32_16x16x32_bf16 v[0:3], v[174:177], v[190:193], v[0:3]
	v_mfma_f32_16x16x32_bf16 v[116:119], v[144:147], v[198:201], v[116:119]
	v_mfma_f32_16x16x32_bf16 v[112:115], v[174:177], v[198:201], v[112:115]
	v_mfma_f32_16x16x32_bf16 v[100:103], v[144:147], v[206:209], v[100:103]
	v_mfma_f32_16x16x32_bf16 v[96:99], v[174:177], v[206:209], v[96:99]
	v_mfma_f32_16x16x32_bf16 v[24:27], v[148:151], v[186:189], v[24:27]
	v_mfma_f32_16x16x32_bf16 v[20:23], v[178:181], v[186:189], v[20:23]
	v_mfma_f32_16x16x32_bf16 v[4:7], v[148:151], v[194:197], v[4:7]
	v_mfma_f32_16x16x32_bf16 v[0:3], v[178:181], v[194:197], v[0:3]
	v_mfma_f32_16x16x32_bf16 v[116:119], v[148:151], v[202:205], v[116:119]
	v_mfma_f32_16x16x32_bf16 v[112:115], v[178:181], v[202:205], v[112:115]
	v_mfma_f32_16x16x32_bf16 v[100:103], v[148:151], v[232:235], v[100:103]
	v_mfma_f32_16x16x32_bf16 v[96:99], v[178:181], v[232:235], v[96:99]
	s_setprio 0
	s_barrier
	s_add_i32 s80, s80, s3
	s_mov_b32 m0, s80
	ds_read_b128 v[182:185], v230 offset:16384
	ds_read_b128 v[186:189], v230 offset:17408
	ds_read_b128 v[190:193], v230 offset:18432
	ds_read_b128 v[194:197], v230 offset:19456
	ds_read_b128 v[198:201], v230 offset:20480
	ds_read_b128 v[202:205], v230 offset:21504
	ds_read_b128 v[206:209], v230 offset:22528
	ds_read_b128 v[232:235], v230 offset:23552
	global_load_lds_dwordx4 v160, s[70:71]
	s_add_i32 m0, s80, 0x2000
	s_add_i32 s69, s69, s3
	global_load_lds_dwordx4 v164, s[70:71]
	s_add_u32 s70, s70, s26
	s_addc_u32 s71, s71, 0
	s_mov_b32 m0, s69
	s_nop 0
	global_load_lds_dwordx4 v160, s[70:71]
	s_add_i32 m0, s69, 0x2000
	s_nop 0
	global_load_lds_dwordx4 v164, s[70:71]
	s_mov_b32 m0, s50
	s_nop 0
	global_load_lds_dwordx4 v158, s[46:47]
	s_mov_b32 m0, s51
	s_nop 0
	global_load_lds_dwordx4 v162, s[46:47]
	s_waitcnt vmcnt(8)
	s_waitcnt lgkmcnt(0)
	s_barrier
	s_setprio 1
	s_waitcnt lgkmcnt(0)
	v_mfma_f32_16x16x32_bf16 v[92:95], v[128:131], v[182:185], v[92:95]
	v_mfma_f32_16x16x32_bf16 v[88:91], v[136:139], v[182:185], v[88:91]
	v_mfma_f32_16x16x32_bf16 v[76:79], v[128:131], v[190:193], v[76:79]
	v_mfma_f32_16x16x32_bf16 v[72:75], v[136:139], v[190:193], v[72:75]
	v_mfma_f32_16x16x32_bf16 v[60:63], v[128:131], v[198:201], v[60:63]
	v_mfma_f32_16x16x32_bf16 v[56:59], v[136:139], v[198:201], v[56:59]
	v_mfma_f32_16x16x32_bf16 v[44:47], v[128:131], v[206:209], v[44:47]
	v_mfma_f32_16x16x32_bf16 v[40:43], v[136:139], v[206:209], v[40:43]
	v_mfma_f32_16x16x32_bf16 v[92:95], v[132:135], v[186:189], v[92:95]
	v_mfma_f32_16x16x32_bf16 v[88:91], v[140:143], v[186:189], v[88:91]
	v_mfma_f32_16x16x32_bf16 v[76:79], v[132:135], v[194:197], v[76:79]
	v_mfma_f32_16x16x32_bf16 v[72:75], v[140:143], v[194:197], v[72:75]
	v_mfma_f32_16x16x32_bf16 v[60:63], v[132:135], v[202:205], v[60:63]
	v_mfma_f32_16x16x32_bf16 v[56:59], v[140:143], v[202:205], v[56:59]
	v_mfma_f32_16x16x32_bf16 v[44:47], v[132:135], v[232:235], v[44:47]
	v_mfma_f32_16x16x32_bf16 v[40:43], v[140:143], v[232:235], v[40:43]
	s_setprio 0
	s_setprio 1
	v_mfma_f32_16x16x32_bf16 v[84:87], v[144:147], v[182:185], v[84:87]
	v_mfma_f32_16x16x32_bf16 v[80:83], v[174:177], v[182:185], v[80:83]
	v_mfma_f32_16x16x32_bf16 v[68:71], v[144:147], v[190:193], v[68:71]
	v_mfma_f32_16x16x32_bf16 v[64:67], v[174:177], v[190:193], v[64:67]
	v_mfma_f32_16x16x32_bf16 v[52:55], v[144:147], v[198:201], v[52:55]
	v_mfma_f32_16x16x32_bf16 v[48:51], v[174:177], v[198:201], v[48:51]
	v_mfma_f32_16x16x32_bf16 v[36:39], v[144:147], v[206:209], v[36:39]
	v_mfma_f32_16x16x32_bf16 v[32:35], v[174:177], v[206:209], v[32:35]
	v_mfma_f32_16x16x32_bf16 v[84:87], v[148:151], v[186:189], v[84:87]
	v_mfma_f32_16x16x32_bf16 v[80:83], v[178:181], v[186:189], v[80:83]
	v_mfma_f32_16x16x32_bf16 v[68:71], v[148:151], v[194:197], v[68:71]
	v_mfma_f32_16x16x32_bf16 v[64:67], v[178:181], v[194:197], v[64:67]
	v_mfma_f32_16x16x32_bf16 v[52:55], v[148:151], v[202:205], v[52:55]
	v_mfma_f32_16x16x32_bf16 v[48:51], v[178:181], v[202:205], v[48:51]
	v_mfma_f32_16x16x32_bf16 v[36:39], v[148:151], v[232:235], v[36:39]
	v_mfma_f32_16x16x32_bf16 v[32:35], v[178:181], v[232:235], v[32:35]
	s_setprio 0
	s_barrier
	ds_read_b128 v[128:131], v238
	ds_read_b128 v[132:135], v238 offset:1024
	ds_read_b128 v[136:139], v238 offset:2048
	ds_read_b128 v[140:143], v238 offset:3072
	ds_read_b128 v[144:147], v239
	ds_read_b128 v[148:151], v239 offset:1024
	ds_read_b128 v[174:177], v239 offset:2048
	ds_read_b128 v[178:181], v239 offset:3072
	s_add_u32 s46, s46, s26
	s_addc_u32 s47, s47, 0
	s_mov_b32 m0, s8
	ds_read_b128 v[182:185], v230 offset:32768
	ds_read_b128 v[186:189], v230 offset:33792
	ds_read_b128 v[190:193], v230 offset:34816
	ds_read_b128 v[194:197], v230 offset:35840
	ds_read_b128 v[198:201], v230 offset:36864
	ds_read_b128 v[202:205], v230 offset:37888
	ds_read_b128 v[206:209], v230 offset:38912
	ds_read_b128 v[232:235], v230 offset:39936
	global_load_lds_dwordx4 v158, s[46:47]
	s_mov_b32 m0, s9
	s_nop 0
	global_load_lds_dwordx4 v162, s[46:47]
	s_waitcnt vmcnt(8)
	s_waitcnt lgkmcnt(0)
	s_barrier
	s_setprio 1
	s_waitcnt lgkmcnt(0)
	v_mfma_f32_16x16x32_bf16 v[16:19], v[128:131], v[182:185], v[16:19]
	v_mfma_f32_16x16x32_bf16 v[28:31], v[136:139], v[182:185], v[28:31]
	v_mfma_f32_16x16x32_bf16 v[12:15], v[128:131], v[190:193], v[12:15]
	v_mfma_f32_16x16x32_bf16 v[8:11], v[136:139], v[190:193], v[8:11]
	v_mfma_f32_16x16x32_bf16 v[124:127], v[128:131], v[198:201], v[124:127]
	v_mfma_f32_16x16x32_bf16 v[120:123], v[136:139], v[198:201], v[120:123]
	v_mfma_f32_16x16x32_bf16 v[108:111], v[128:131], v[206:209], v[108:111]
	v_mfma_f32_16x16x32_bf16 v[104:107], v[136:139], v[206:209], v[104:107]
	v_mfma_f32_16x16x32_bf16 v[16:19], v[132:135], v[186:189], v[16:19]
	v_mfma_f32_16x16x32_bf16 v[28:31], v[140:143], v[186:189], v[28:31]
	v_mfma_f32_16x16x32_bf16 v[12:15], v[132:135], v[194:197], v[12:15]
	v_mfma_f32_16x16x32_bf16 v[8:11], v[140:143], v[194:197], v[8:11]
	v_mfma_f32_16x16x32_bf16 v[124:127], v[132:135], v[202:205], v[124:127]
	v_mfma_f32_16x16x32_bf16 v[120:123], v[140:143], v[202:205], v[120:123]
	v_mfma_f32_16x16x32_bf16 v[108:111], v[132:135], v[232:235], v[108:111]
	v_mfma_f32_16x16x32_bf16 v[104:107], v[140:143], v[232:235], v[104:107]
	s_setprio 0
	s_setprio 1
	v_mfma_f32_16x16x32_bf16 v[24:27], v[144:147], v[182:185], v[24:27]
	v_mfma_f32_16x16x32_bf16 v[20:23], v[174:177], v[182:185], v[20:23]
	v_mfma_f32_16x16x32_bf16 v[4:7], v[144:147], v[190:193], v[4:7]
	v_mfma_f32_16x16x32_bf16 v[0:3], v[174:177], v[190:193], v[0:3]
	v_mfma_f32_16x16x32_bf16 v[116:119], v[144:147], v[198:201], v[116:119]
	v_mfma_f32_16x16x32_bf16 v[112:115], v[174:177], v[198:201], v[112:115]
	v_mfma_f32_16x16x32_bf16 v[100:103], v[144:147], v[206:209], v[100:103]
	v_mfma_f32_16x16x32_bf16 v[96:99], v[174:177], v[206:209], v[96:99]
	v_mfma_f32_16x16x32_bf16 v[24:27], v[148:151], v[186:189], v[24:27]
	v_mfma_f32_16x16x32_bf16 v[20:23], v[178:181], v[186:189], v[20:23]
	v_mfma_f32_16x16x32_bf16 v[4:7], v[148:151], v[194:197], v[4:7]
	v_mfma_f32_16x16x32_bf16 v[0:3], v[178:181], v[194:197], v[0:3]
	v_mfma_f32_16x16x32_bf16 v[116:119], v[148:151], v[202:205], v[116:119]
	v_mfma_f32_16x16x32_bf16 v[112:115], v[178:181], v[202:205], v[112:115]
	v_mfma_f32_16x16x32_bf16 v[100:103], v[148:151], v[232:235], v[100:103]
	v_mfma_f32_16x16x32_bf16 v[96:99], v[178:181], v[232:235], v[96:99]
	s_setprio 0
	s_barrier
	s_add_u32 vcc_lo, s70, s6
	s_addc_u32 vcc_hi, s71, s7
	s_sub_u32 vcc_lo, vcc_lo, s26
	s_subb_u32 vcc_hi, vcc_hi, 0
	s_add_i32 m0, s3, 0x18000
	ds_read_b128 v[182:185], v230 offset:49152
	ds_read_b128 v[186:189], v230 offset:50176
	ds_read_b128 v[190:193], v230 offset:51200
	ds_read_b128 v[194:197], v230 offset:52224
	ds_read_b128 v[198:201], v230 offset:53248
	ds_read_b128 v[202:205], v230 offset:54272
	ds_read_b128 v[206:209], v230 offset:55296
	ds_read_b128 v[232:235], v230 offset:56320
	global_load_lds_dwordx4 v160, vcc
	s_add_i32 m0, s3, 0x1a000
	s_nop 0
	global_load_lds_dwordx4 v164, vcc
	s_add_u32 vcc_lo, vcc_lo, s26
	s_addc_u32 vcc_hi, vcc_hi, 0
	s_add_i32 m0, s3, 0x1c000
	s_nop 0
	global_load_lds_dwordx4 v160, vcc
	s_add_i32 m0, s3, 0x1e000
	s_nop 0
	global_load_lds_dwordx4 v164, vcc
	s_add_u32 vcc_lo, s46, s6
	s_addc_u32 vcc_hi, s47, s7
	s_sub_u32 vcc_lo, vcc_lo, s26
	s_subb_u32 vcc_hi, vcc_hi, 0
	s_mov_b32 m0, s30
	s_nop 0
	global_load_lds_dwordx4 v158, vcc
	s_mov_b32 m0, s31
	s_nop 0
	global_load_lds_dwordx4 v162, vcc
	s_waitcnt vmcnt(8)
	s_waitcnt lgkmcnt(0)
	s_barrier
	s_setprio 1
	s_waitcnt lgkmcnt(0)
	v_mfma_f32_16x16x32_bf16 v[92:95], v[128:131], v[182:185], v[92:95]
	v_mfma_f32_16x16x32_bf16 v[88:91], v[136:139], v[182:185], v[88:91]
	v_mfma_f32_16x16x32_bf16 v[76:79], v[128:131], v[190:193], v[76:79]
	v_mfma_f32_16x16x32_bf16 v[72:75], v[136:139], v[190:193], v[72:75]
	v_mfma_f32_16x16x32_bf16 v[60:63], v[128:131], v[198:201], v[60:63]
	v_mfma_f32_16x16x32_bf16 v[56:59], v[136:139], v[198:201], v[56:59]
	v_mfma_f32_16x16x32_bf16 v[44:47], v[128:131], v[206:209], v[44:47]
	v_mfma_f32_16x16x32_bf16 v[40:43], v[136:139], v[206:209], v[40:43]
	v_mfma_f32_16x16x32_bf16 v[92:95], v[132:135], v[186:189], v[92:95]
	v_mfma_f32_16x16x32_bf16 v[88:91], v[140:143], v[186:189], v[88:91]
	v_mfma_f32_16x16x32_bf16 v[76:79], v[132:135], v[194:197], v[76:79]
	v_mfma_f32_16x16x32_bf16 v[72:75], v[140:143], v[194:197], v[72:75]
	v_mfma_f32_16x16x32_bf16 v[60:63], v[132:135], v[202:205], v[60:63]
	v_mfma_f32_16x16x32_bf16 v[56:59], v[140:143], v[202:205], v[56:59]
	v_mfma_f32_16x16x32_bf16 v[44:47], v[132:135], v[232:235], v[44:47]
	v_mfma_f32_16x16x32_bf16 v[40:43], v[140:143], v[232:235], v[40:43]
	s_setprio 0
	s_setprio 1
	v_mfma_f32_16x16x32_bf16 v[84:87], v[144:147], v[182:185], v[84:87]
	v_mfma_f32_16x16x32_bf16 v[80:83], v[174:177], v[182:185], v[80:83]
	v_mfma_f32_16x16x32_bf16 v[68:71], v[144:147], v[190:193], v[68:71]
	v_mfma_f32_16x16x32_bf16 v[64:67], v[174:177], v[190:193], v[64:67]
	v_mfma_f32_16x16x32_bf16 v[52:55], v[144:147], v[198:201], v[52:55]
	v_mfma_f32_16x16x32_bf16 v[48:51], v[174:177], v[198:201], v[48:51]
	v_mfma_f32_16x16x32_bf16 v[36:39], v[144:147], v[206:209], v[36:39]
	v_mfma_f32_16x16x32_bf16 v[32:35], v[174:177], v[206:209], v[32:35]
	v_mfma_f32_16x16x32_bf16 v[84:87], v[148:151], v[186:189], v[84:87]
	v_mfma_f32_16x16x32_bf16 v[80:83], v[178:181], v[186:189], v[80:83]
	v_mfma_f32_16x16x32_bf16 v[68:71], v[148:151], v[194:197], v[68:71]
	v_mfma_f32_16x16x32_bf16 v[64:67], v[178:181], v[194:197], v[64:67]
	v_mfma_f32_16x16x32_bf16 v[52:55], v[148:151], v[202:205], v[52:55]
	v_mfma_f32_16x16x32_bf16 v[48:51], v[178:181], v[202:205], v[48:51]
	v_mfma_f32_16x16x32_bf16 v[36:39], v[148:151], v[232:235], v[36:39]
	v_mfma_f32_16x16x32_bf16 v[32:35], v[178:181], v[232:235], v[32:35]
	s_setprio 0
	s_barrier
	s_add_u32 s44, s44, 0x100
	s_addc_u32 s45, s45, 0
	s_add_u32 s23, s23, 0x100
	s_addc_u32 s48, s48, 0
	s_cmp_ge_u32 s49, s88
	s_mov_b32 s46, s49
	s_cbranch_scc0 .LBB0_248
